# residual-add epilogues: permlane swaps removed, the LDS transpose works directly on the native accumulator lane layout (two 8-byte LDS accesses per 16 bytes)
# baseline (speedup 1.0000x reference)
; __device__ __forceinline__ unsigned cvt_pk_bf16(float lo, float hi) { f32x2_t v = {lo, hi}; bf16x2_t b = __builtin_convertvector(v, bf16x2_t); return __builtin_bit_cast(unsigned, b); }
;     __device__ __forceinline__ void operator()(const f32x4 (&acc)[2][2][4][2], const Unit& u, int wr, int wc, int fr, int fq) const {
;         typedef unsigned u32x2v __attribute__((ext_vector_type(2)));
;         const int row0 = u.pm * BM + wr * 64 + fr, col0 = u.pn * BM + wc * 32 + 4 * fq;
;         u32x2v bs[2][4][2][2];
; #pragma unroll
;         for (int ai = 0; ai < 2; ++ai)
; #pragma unroll
;             for (int m = 0; m < 4; ++m)
; #pragma unroll
;                 for (int bj = 0; bj < 2; ++bj)
; #pragma unroll
;                     for (int n = 0; n < 2; ++n) bs[ai][m][bj][n] = *(const u32x2v*)(hb + (size_t)(row0 + ai * HALF + m * 16) * 1024 + col0 + bj * HALF + n * 16);
; #pragma unroll
;         for (int ai = 0; ai < 2; ++ai)
; #pragma unroll
;             for (int m = 0; m < 4; ++m) { const int row = row0 + ai * HALF + m * 16; const size_t off = (size_t)row * 1024 + col0; float q = 0.f;
; #pragma unroll
;                 for (int bj = 0; bj < 2; ++bj)
; #pragma unroll
;                     for (int n = 0; n < 2; ++n) { const size_t o2 = off + bj * HALF + n * 16; const u32x2v b = bs[ai][m][bj][n];
;                         const f32x4 bf = {__builtin_bit_cast(float, b.x << 16), __builtin_bit_cast(float, b.x & 0xffff0000u), __builtin_bit_cast(float, b.y << 16), __builtin_bit_cast(float, b.y & 0xffff0000u)};
;                         const f32x4 o = bf + acc[ai][bj][m][n];
;                         u32x2v w; w.x = cvt_pk_bf16(o[0], o[1]); w.y = cvt_pk_bf16(o[2], o[3]); *(u32x2v*)(hb + o2) = w;
;                         q += (o[0] * o[0] + o[1] * o[1]) + (o[2] * o[2] + o[3] * o[3]); }
.LBB0_523:
	s_lshl_b32 s6, s24, 8
	s_add_i32 s6, s6, s16
	v_lshrrev_b32_e32 v136, 2, v242
	v_add_u32_e32 v136, s6, v136
	v_and_b32_e32 v138, 0x60, v230
	v_lshl_or_b32 v138, s23, 8, v138
	v_lshlrev_b32_e32 v138, 1, v138
	v_and_b32_e32 v139, 3, v242
	v_lshl_or_b32 v138, v139, 4, v138
	v_lshl_or_b32 v140, v136, 11, v138
	v_mov_b32_e32 v141, 0
	v_lshl_add_u64 v[212:213], s[84:85], 0, v[140:141]
	s_mov_b64 s[6:7], 0x8000
	v_lshl_add_u64 v[214:215], v[212:213], 0, s[6:7]
	s_mov_b64 s[6:7], 0x10000
	v_lshl_add_u64 v[216:217], v[212:213], 0, s[6:7]
	s_mov_b64 s[6:7], 0x18000
	v_lshl_add_u64 v[218:219], v[212:213], 0, s[6:7]
	s_mov_b64 s[6:7], 0x40000
	v_lshl_add_u64 v[220:221], v[212:213], 0, s[6:7]
	s_mov_b64 s[6:7], 0x48000
	v_lshl_add_u64 v[222:223], v[212:213], 0, s[6:7]
	s_mov_b64 s[6:7], 0x50000
	v_lshl_add_u64 v[224:225], v[212:213], 0, s[6:7]
	s_mov_b64 s[6:7], 0x58000
	v_lshl_add_u64 v[226:227], v[212:213], 0, s[6:7]
	global_load_dwordx4 v[144:147], v[212:213], off
	global_load_dwordx4 v[148:151], v[212:213], off offset:256
	global_load_dwordx4 v[152:155], v[214:215], off
	global_load_dwordx4 v[156:159], v[214:215], off offset:256
	global_load_dwordx4 v[160:163], v[216:217], off
	global_load_dwordx4 v[168:171], v[216:217], off offset:256
	global_load_dwordx4 v[172:175], v[218:219], off
	global_load_dwordx4 v[176:179], v[218:219], off offset:256
	global_load_dwordx4 v[180:183], v[220:221], off
	global_load_dwordx4 v[184:187], v[220:221], off offset:256
	global_load_dwordx4 v[188:191], v[222:223], off
	global_load_dwordx4 v[192:195], v[222:223], off offset:256
	global_load_dwordx4 v[196:199], v[224:225], off
	global_load_dwordx4 v[200:203], v[224:225], off offset:256
	global_load_dwordx4 v[204:207], v[226:227], off
	global_load_dwordx4 v[208:211], v[226:227], off offset:256
	v_lshrrev_b32_e32 v136, 2, v242
	v_and_b32_e32 v137, 3, v242
	v_lshrrev_b32_e32 v138, 2, v136
	v_xor_b32_e32 v137, v137, v138
	v_lshlrev_b32_e32 v137, 4, v137
	v_lshl_or_b32 v234, v136, 6, v137
	v_bfe_u32 v136, v230, 2, 1
	v_bfe_u32 v137, v230, 3, 1
	v_lshrrev_b32_e32 v138, 2, v228
	v_xor_b32_e32 v137, v137, v138
	v_lshlrev_b32_e32 v137, 4, v137
	v_lshl_or_b32 v137, v136, 3, v137
	v_lshl_or_b32 v235, v228, 6, v137
	s_lshl_b32 s6, s12, 10
	s_lshl_b32 s7, s16, 6
	s_add_i32 s6, s6, s7
	s_add_i32 s6, s6, 0x23000
	v_add_u32_e32 v234, s6, v234
	v_add_u32_e32 v235, s6, v235
	v_xor_b32_e32 v240, 32, v235
	v_xor_b32_e32 v232, 16, v242
	v_lshlrev_b32_e32 v232, 2, v232
	v_xor_b32_e32 v233, 32, v242
	v_lshlrev_b32_e32 v233, 2, v233
	s_waitcnt vmcnt(15)
	ds_write_b128 v234, v[144:147]
	ds_read_b64 v[144:145], v235
	ds_read_b64 v[146:147], v240
	s_waitcnt vmcnt(14)
	ds_write_b128 v234, v[148:151]
	ds_read_b64 v[148:149], v235
	ds_read_b64 v[150:151], v240
	s_waitcnt lgkmcnt(3)
	v_lshlrev_b32_e32 v140, 16, v144
	v_and_b32_e32 v141, 0xffff0000, v144
	v_lshlrev_b32_e32 v142, 16, v145
	v_and_b32_e32 v143, 0xffff0000, v145
	v_pk_add_f32 v[126:127], v[126:127], v[140:141]
	v_pk_add_f32 v[128:129], v[128:129], v[142:143]
	v_lshlrev_b32_e32 v140, 16, v146
	v_and_b32_e32 v141, 0xffff0000, v146
	v_lshlrev_b32_e32 v142, 16, v147
	v_and_b32_e32 v143, 0xffff0000, v147
	v_pk_add_f32 v[122:123], v[122:123], v[140:141]
	v_pk_add_f32 v[124:125], v[124:125], v[142:143]
	v_cvt_pk_bf16_f32 v144, v126, v127
	v_cvt_pk_bf16_f32 v145, v128, v129
	v_cvt_pk_bf16_f32 v146, v122, v123
	v_cvt_pk_bf16_f32 v147, v124, v125
	ds_write_b64 v235, v[144:145]
	ds_write_b64 v240, v[146:147]
	ds_read_b128 v[144:147], v234
	s_waitcnt vmcnt(13)
	ds_write_b128 v234, v[152:155]
	ds_read_b64 v[152:153], v235
	ds_read_b64 v[154:155], v240
	v_mul_f32_e32 v140, v126, v126
	v_mul_f32_e32 v141, v122, v122
	v_fmac_f32_e32 v140, v127, v127
	v_fmac_f32_e32 v141, v123, v123
	v_fmac_f32_e32 v140, v128, v128
	v_fmac_f32_e32 v141, v124, v124
	v_fmac_f32_e32 v140, v129, v129
	v_fmac_f32_e32 v141, v125, v125
	v_add_f32_e32 v138, v140, v141
	s_waitcnt lgkmcnt(3)
	global_store_dwordx4 v[212:213], v[144:147], off
	v_lshlrev_b32_e32 v140, 16, v148
	v_and_b32_e32 v141, 0xffff0000, v148
	v_lshlrev_b32_e32 v142, 16, v149
	v_and_b32_e32 v143, 0xffff0000, v149
	v_pk_add_f32 v[118:119], v[118:119], v[140:141]
	v_pk_add_f32 v[120:121], v[120:121], v[142:143]
	v_lshlrev_b32_e32 v140, 16, v150
	v_and_b32_e32 v141, 0xffff0000, v150
	v_lshlrev_b32_e32 v142, 16, v151
	v_and_b32_e32 v143, 0xffff0000, v151
	v_pk_add_f32 v[114:115], v[114:115], v[140:141]
	v_pk_add_f32 v[116:117], v[116:117], v[142:143]
	v_cvt_pk_bf16_f32 v148, v118, v119
	v_cvt_pk_bf16_f32 v149, v120, v121
	v_cvt_pk_bf16_f32 v150, v114, v115
	v_cvt_pk_bf16_f32 v151, v116, v117
	ds_write_b64 v235, v[148:149]
	ds_write_b64 v240, v[150:151]
	ds_read_b128 v[148:151], v234
	s_waitcnt vmcnt(13)
	ds_write_b128 v234, v[156:159]
	ds_read_b64 v[156:157], v235
	ds_read_b64 v[158:159], v240
	v_mul_f32_e32 v140, v118, v118
	v_mul_f32_e32 v141, v114, v114
	v_fmac_f32_e32 v140, v119, v119
	v_fmac_f32_e32 v141, v115, v115
	v_fmac_f32_e32 v140, v120, v120
	v_fmac_f32_e32 v141, v116, v116
	v_fmac_f32_e32 v140, v121, v121
	v_fmac_f32_e32 v141, v117, v117
	v_add_f32_e32 v139, v140, v141
	v_add_f32_e32 v126, v138, v139
	s_waitcnt lgkmcnt(3)
	global_store_dwordx4 v[212:213], v[148:151], off offset:256
	v_lshlrev_b32_e32 v140, 16, v152
	v_and_b32_e32 v141, 0xffff0000, v152
	v_lshlrev_b32_e32 v142, 16, v153
	v_and_b32_e32 v143, 0xffff0000, v153
	v_pk_add_f32 v[110:111], v[110:111], v[140:141]
	v_pk_add_f32 v[112:113], v[112:113], v[142:143]
	v_lshlrev_b32_e32 v140, 16, v154
	v_and_b32_e32 v141, 0xffff0000, v154
	v_lshlrev_b32_e32 v142, 16, v155
	v_and_b32_e32 v143, 0xffff0000, v155
	v_pk_add_f32 v[106:107], v[106:107], v[140:141]
	v_pk_add_f32 v[108:109], v[108:109], v[142:143]
	v_cvt_pk_bf16_f32 v152, v110, v111
	v_cvt_pk_bf16_f32 v153, v112, v113
	v_cvt_pk_bf16_f32 v154, v106, v107
	v_cvt_pk_bf16_f32 v155, v108, v109
	ds_write_b64 v235, v[152:153]
	ds_write_b64 v240, v[154:155]
	ds_read_b128 v[152:155], v234
	s_waitcnt vmcnt(13)
; __device__ __forceinline__ unsigned cvt_pk_bf16(float lo, float hi) { f32x2_t v = {lo, hi}; bf16x2_t b = __builtin_convertvector(v, bf16x2_t); return __builtin_bit_cast(unsigned, b); }
;     __device__ __forceinline__ void operator()(const f32x4 (&acc)[2][2][4][2], const Unit& u, int wr, int wc, int fr, int fq) const {
;     ...
;         for (int ai = 0; ai < 2; ++ai)
; #pragma unroll
;             for (int m = 0; m < 4; ++m) { const int row = row0 + ai * HALF + m * 16; const size_t off = (size_t)row * 1024 + col0; float q = 0.f;
; #pragma unroll
;                 for (int bj = 0; bj < 2; ++bj)
; #pragma unroll
;                     for (int n = 0; n < 2; ++n) { const size_t o2 = off + bj * HALF + n * 16; const u32x2v b = bs[ai][m][bj][n];
;                         const f32x4 bf = {__builtin_bit_cast(float, b.x << 16), __builtin_bit_cast(float, b.x & 0xffff0000u), __builtin_bit_cast(float, b.y << 16), __builtin_bit_cast(float, b.y & 0xffff0000u)};
;                         const f32x4 o = bf + acc[ai][bj][m][n];
;                         u32x2v w; w.x = cvt_pk_bf16(o[0], o[1]); w.y = cvt_pk_bf16(o[2], o[3]); *(u32x2v*)(hb + o2) = w;
;                         q += (o[0] * o[0] + o[1] * o[1]) + (o[2] * o[2] + o[3] * o[3]); }
	ds_write_b128 v234, v[160:163]
	ds_read_b64 v[160:161], v235
	ds_read_b64 v[162:163], v240
	v_mul_f32_e32 v140, v110, v110
	v_mul_f32_e32 v141, v106, v106
	v_fmac_f32_e32 v140, v111, v111
	v_fmac_f32_e32 v141, v107, v107
	v_fmac_f32_e32 v140, v112, v112
	v_fmac_f32_e32 v141, v108, v108
	v_fmac_f32_e32 v140, v113, v113
	v_fmac_f32_e32 v141, v109, v109
	v_add_f32_e32 v138, v140, v141
	s_waitcnt lgkmcnt(3)
	global_store_dwordx4 v[214:215], v[152:155], off
	v_lshlrev_b32_e32 v140, 16, v156
	v_and_b32_e32 v141, 0xffff0000, v156
	v_lshlrev_b32_e32 v142, 16, v157
	v_and_b32_e32 v143, 0xffff0000, v157
	v_pk_add_f32 v[102:103], v[102:103], v[140:141]
	v_pk_add_f32 v[104:105], v[104:105], v[142:143]
	v_lshlrev_b32_e32 v140, 16, v158
	v_and_b32_e32 v141, 0xffff0000, v158
	v_lshlrev_b32_e32 v142, 16, v159
	v_and_b32_e32 v143, 0xffff0000, v159
	v_pk_add_f32 v[98:99], v[98:99], v[140:141]
	v_pk_add_f32 v[100:101], v[100:101], v[142:143]
	v_cvt_pk_bf16_f32 v156, v102, v103
	v_cvt_pk_bf16_f32 v157, v104, v105
	v_cvt_pk_bf16_f32 v158, v98, v99
	v_cvt_pk_bf16_f32 v159, v100, v101
	ds_write_b64 v235, v[156:157]
	ds_write_b64 v240, v[158:159]
	ds_read_b128 v[156:159], v234
	s_waitcnt vmcnt(13)
	ds_write_b128 v234, v[168:171]
	ds_read_b64 v[168:169], v235
	ds_read_b64 v[170:171], v240
	v_mul_f32_e32 v140, v102, v102
	v_mul_f32_e32 v141, v98, v98
	v_fmac_f32_e32 v140, v103, v103
	v_fmac_f32_e32 v141, v99, v99
	v_fmac_f32_e32 v140, v104, v104
	v_fmac_f32_e32 v141, v100, v100
	v_fmac_f32_e32 v140, v105, v105
	v_fmac_f32_e32 v141, v101, v101
	v_add_f32_e32 v139, v140, v141
	v_add_f32_e32 v110, v138, v139
	s_waitcnt lgkmcnt(3)
	global_store_dwordx4 v[214:215], v[156:159], off offset:256
	v_lshlrev_b32_e32 v140, 16, v160
	v_and_b32_e32 v141, 0xffff0000, v160
	v_lshlrev_b32_e32 v142, 16, v161
	v_and_b32_e32 v143, 0xffff0000, v161
	v_pk_add_f32 v[94:95], v[94:95], v[140:141]
	v_pk_add_f32 v[96:97], v[96:97], v[142:143]
	v_lshlrev_b32_e32 v140, 16, v162
	v_and_b32_e32 v141, 0xffff0000, v162
	v_lshlrev_b32_e32 v142, 16, v163
	v_and_b32_e32 v143, 0xffff0000, v163
	v_pk_add_f32 v[90:91], v[90:91], v[140:141]
	v_pk_add_f32 v[92:93], v[92:93], v[142:143]
	v_cvt_pk_bf16_f32 v160, v94, v95
	v_cvt_pk_bf16_f32 v161, v96, v97
	v_cvt_pk_bf16_f32 v162, v90, v91
	v_cvt_pk_bf16_f32 v163, v92, v93
	ds_write_b64 v235, v[160:161]
	ds_write_b64 v240, v[162:163]
	ds_read_b128 v[160:163], v234
	s_waitcnt vmcnt(13)
	ds_write_b128 v234, v[172:175]
	ds_read_b64 v[172:173], v235
	ds_read_b64 v[174:175], v240
	v_mul_f32_e32 v140, v94, v94
	v_mul_f32_e32 v141, v90, v90
	v_fmac_f32_e32 v140, v95, v95
	v_fmac_f32_e32 v141, v91, v91
	v_fmac_f32_e32 v140, v96, v96
	v_fmac_f32_e32 v141, v92, v92
	v_fmac_f32_e32 v140, v97, v97
	v_fmac_f32_e32 v141, v93, v93
	v_add_f32_e32 v138, v140, v141
	s_waitcnt lgkmcnt(3)
	global_store_dwordx4 v[216:217], v[160:163], off
	v_lshlrev_b32_e32 v140, 16, v168
	v_and_b32_e32 v141, 0xffff0000, v168
	v_lshlrev_b32_e32 v142, 16, v169
	v_and_b32_e32 v143, 0xffff0000, v169
	v_pk_add_f32 v[86:87], v[86:87], v[140:141]
	v_pk_add_f32 v[88:89], v[88:89], v[142:143]
	v_lshlrev_b32_e32 v140, 16, v170
	v_and_b32_e32 v141, 0xffff0000, v170
	v_lshlrev_b32_e32 v142, 16, v171
	v_and_b32_e32 v143, 0xffff0000, v171
	v_pk_add_f32 v[82:83], v[82:83], v[140:141]
	v_pk_add_f32 v[84:85], v[84:85], v[142:143]
	v_cvt_pk_bf16_f32 v168, v86, v87
	v_cvt_pk_bf16_f32 v169, v88, v89
	v_cvt_pk_bf16_f32 v170, v82, v83
	v_cvt_pk_bf16_f32 v171, v84, v85
	ds_write_b64 v235, v[168:169]
	ds_write_b64 v240, v[170:171]
	ds_read_b128 v[168:171], v234
	s_waitcnt vmcnt(13)
	ds_write_b128 v234, v[176:179]
	ds_read_b64 v[176:177], v235
	ds_read_b64 v[178:179], v240
	v_mul_f32_e32 v140, v86, v86
	v_mul_f32_e32 v141, v82, v82
	v_fmac_f32_e32 v140, v87, v87
	v_fmac_f32_e32 v141, v83, v83
	v_fmac_f32_e32 v140, v88, v88
	v_fmac_f32_e32 v141, v84, v84
	v_fmac_f32_e32 v140, v89, v89
	v_fmac_f32_e32 v141, v85, v85
	v_add_f32_e32 v139, v140, v141
	v_add_f32_e32 v94, v138, v139
	s_waitcnt lgkmcnt(3)
	global_store_dwordx4 v[216:217], v[168:171], off offset:256
	v_lshlrev_b32_e32 v140, 16, v172
	v_and_b32_e32 v141, 0xffff0000, v172
	v_lshlrev_b32_e32 v142, 16, v173
	v_and_b32_e32 v143, 0xffff0000, v173
	v_pk_add_f32 v[78:79], v[78:79], v[140:141]
	v_pk_add_f32 v[80:81], v[80:81], v[142:143]
	v_lshlrev_b32_e32 v140, 16, v174
	v_and_b32_e32 v141, 0xffff0000, v174
	v_lshlrev_b32_e32 v142, 16, v175
	v_and_b32_e32 v143, 0xffff0000, v175
	v_pk_add_f32 v[74:75], v[74:75], v[140:141]
	v_pk_add_f32 v[76:77], v[76:77], v[142:143]
	v_cvt_pk_bf16_f32 v172, v78, v79
	v_cvt_pk_bf16_f32 v173, v80, v81
	v_cvt_pk_bf16_f32 v174, v74, v75
	v_cvt_pk_bf16_f32 v175, v76, v77
	ds_write_b64 v235, v[172:173]
	ds_write_b64 v240, v[174:175]
	ds_read_b128 v[172:175], v234
	s_waitcnt vmcnt(13)
	ds_write_b128 v234, v[180:183]
	ds_read_b64 v[180:181], v235
	ds_read_b64 v[182:183], v240
	v_mul_f32_e32 v140, v78, v78
	v_mul_f32_e32 v141, v74, v74
	v_fmac_f32_e32 v140, v79, v79
	v_fmac_f32_e32 v141, v75, v75
	v_fmac_f32_e32 v140, v80, v80
	v_fmac_f32_e32 v141, v76, v76
	v_fmac_f32_e32 v140, v81, v81
	v_fmac_f32_e32 v141, v77, v77
	v_add_f32_e32 v138, v140, v141
	s_waitcnt lgkmcnt(3)
	global_store_dwordx4 v[218:219], v[172:175], off
	v_lshlrev_b32_e32 v140, 16, v176
	v_and_b32_e32 v141, 0xffff0000, v176
	v_lshlrev_b32_e32 v142, 16, v177
	v_and_b32_e32 v143, 0xffff0000, v177
	v_pk_add_f32 v[70:71], v[70:71], v[140:141]
	v_pk_add_f32 v[72:73], v[72:73], v[142:143]
	v_lshlrev_b32_e32 v140, 16, v178
	v_and_b32_e32 v141, 0xffff0000, v178
	v_lshlrev_b32_e32 v142, 16, v179
	v_and_b32_e32 v143, 0xffff0000, v179
	v_pk_add_f32 v[66:67], v[66:67], v[140:141]
	v_pk_add_f32 v[68:69], v[68:69], v[142:143]
	v_cvt_pk_bf16_f32 v176, v70, v71
	v_cvt_pk_bf16_f32 v177, v72, v73
	v_cvt_pk_bf16_f32 v178, v66, v67
	v_cvt_pk_bf16_f32 v179, v68, v69
	ds_write_b64 v235, v[176:177]
	ds_write_b64 v240, v[178:179]
	ds_read_b128 v[176:179], v234
	s_waitcnt vmcnt(13)
; __device__ __forceinline__ unsigned cvt_pk_bf16(float lo, float hi) { f32x2_t v = {lo, hi}; bf16x2_t b = __builtin_convertvector(v, bf16x2_t); return __builtin_bit_cast(unsigned, b); }
;     __device__ __forceinline__ void operator()(const f32x4 (&acc)[2][2][4][2], const Unit& u, int wr, int wc, int fr, int fq) const {
;     ...
;         for (int ai = 0; ai < 2; ++ai)
; #pragma unroll
;             for (int m = 0; m < 4; ++m) { const int row = row0 + ai * HALF + m * 16; const size_t off = (size_t)row * 1024 + col0; float q = 0.f;
; #pragma unroll
;                 for (int bj = 0; bj < 2; ++bj)
; #pragma unroll
;                     for (int n = 0; n < 2; ++n) { const size_t o2 = off + bj * HALF + n * 16; const u32x2v b = bs[ai][m][bj][n];
;                         const f32x4 bf = {__builtin_bit_cast(float, b.x << 16), __builtin_bit_cast(float, b.x & 0xffff0000u), __builtin_bit_cast(float, b.y << 16), __builtin_bit_cast(float, b.y & 0xffff0000u)};
;                         const f32x4 o = bf + acc[ai][bj][m][n];
;                         u32x2v w; w.x = cvt_pk_bf16(o[0], o[1]); w.y = cvt_pk_bf16(o[2], o[3]); *(u32x2v*)(hb + o2) = w;
;                         q += (o[0] * o[0] + o[1] * o[1]) + (o[2] * o[2] + o[3] * o[3]); }
	ds_write_b128 v234, v[184:187]
	ds_read_b64 v[184:185], v235
	ds_read_b64 v[186:187], v240
	v_mul_f32_e32 v140, v70, v70
	v_mul_f32_e32 v141, v66, v66
	v_fmac_f32_e32 v140, v71, v71
	v_fmac_f32_e32 v141, v67, v67
	v_fmac_f32_e32 v140, v72, v72
	v_fmac_f32_e32 v141, v68, v68
	v_fmac_f32_e32 v140, v73, v73
	v_fmac_f32_e32 v141, v69, v69
	v_add_f32_e32 v139, v140, v141
	v_add_f32_e32 v78, v138, v139
	s_waitcnt lgkmcnt(3)
	global_store_dwordx4 v[218:219], v[176:179], off offset:256
	v_lshlrev_b32_e32 v140, 16, v180
	v_and_b32_e32 v141, 0xffff0000, v180
	v_lshlrev_b32_e32 v142, 16, v181
	v_and_b32_e32 v143, 0xffff0000, v181
	v_pk_add_f32 v[62:63], v[62:63], v[140:141]
	v_pk_add_f32 v[64:65], v[64:65], v[142:143]
	v_lshlrev_b32_e32 v140, 16, v182
	v_and_b32_e32 v141, 0xffff0000, v182
	v_lshlrev_b32_e32 v142, 16, v183
	v_and_b32_e32 v143, 0xffff0000, v183
	v_pk_add_f32 v[58:59], v[58:59], v[140:141]
	v_pk_add_f32 v[60:61], v[60:61], v[142:143]
	v_cvt_pk_bf16_f32 v180, v62, v63
	v_cvt_pk_bf16_f32 v181, v64, v65
	v_cvt_pk_bf16_f32 v182, v58, v59
	v_cvt_pk_bf16_f32 v183, v60, v61
	ds_write_b64 v235, v[180:181]
	ds_write_b64 v240, v[182:183]
	ds_read_b128 v[180:183], v234
	s_waitcnt vmcnt(13)
	ds_write_b128 v234, v[188:191]
	ds_read_b64 v[188:189], v235
	ds_read_b64 v[190:191], v240
	v_mul_f32_e32 v140, v62, v62
	v_mul_f32_e32 v141, v58, v58
	v_fmac_f32_e32 v140, v63, v63
	v_fmac_f32_e32 v141, v59, v59
	v_fmac_f32_e32 v140, v64, v64
	v_fmac_f32_e32 v141, v60, v60
	v_fmac_f32_e32 v140, v65, v65
	v_fmac_f32_e32 v141, v61, v61
	v_add_f32_e32 v138, v140, v141
	s_waitcnt lgkmcnt(3)
	global_store_dwordx4 v[220:221], v[180:183], off
	v_lshlrev_b32_e32 v140, 16, v184
	v_and_b32_e32 v141, 0xffff0000, v184
	v_lshlrev_b32_e32 v142, 16, v185
	v_and_b32_e32 v143, 0xffff0000, v185
	v_pk_add_f32 v[54:55], v[54:55], v[140:141]
	v_pk_add_f32 v[56:57], v[56:57], v[142:143]
	v_lshlrev_b32_e32 v140, 16, v186
	v_and_b32_e32 v141, 0xffff0000, v186
	v_lshlrev_b32_e32 v142, 16, v187
	v_and_b32_e32 v143, 0xffff0000, v187
	v_pk_add_f32 v[50:51], v[50:51], v[140:141]
	v_pk_add_f32 v[52:53], v[52:53], v[142:143]
	v_cvt_pk_bf16_f32 v184, v54, v55
	v_cvt_pk_bf16_f32 v185, v56, v57
	v_cvt_pk_bf16_f32 v186, v50, v51
	v_cvt_pk_bf16_f32 v187, v52, v53
	ds_write_b64 v235, v[184:185]
	ds_write_b64 v240, v[186:187]
	ds_read_b128 v[184:187], v234
	s_waitcnt vmcnt(13)
	ds_write_b128 v234, v[192:195]
	ds_read_b64 v[192:193], v235
	ds_read_b64 v[194:195], v240
	v_mul_f32_e32 v140, v54, v54
	v_mul_f32_e32 v141, v50, v50
	v_fmac_f32_e32 v140, v55, v55
	v_fmac_f32_e32 v141, v51, v51
	v_fmac_f32_e32 v140, v56, v56
	v_fmac_f32_e32 v141, v52, v52
	v_fmac_f32_e32 v140, v57, v57
	v_fmac_f32_e32 v141, v53, v53
	v_add_f32_e32 v139, v140, v141
	v_add_f32_e32 v62, v138, v139
	s_waitcnt lgkmcnt(3)
	global_store_dwordx4 v[220:221], v[184:187], off offset:256
	v_lshlrev_b32_e32 v140, 16, v188
	v_and_b32_e32 v141, 0xffff0000, v188
	v_lshlrev_b32_e32 v142, 16, v189
	v_and_b32_e32 v143, 0xffff0000, v189
	v_pk_add_f32 v[46:47], v[46:47], v[140:141]
	v_pk_add_f32 v[48:49], v[48:49], v[142:143]
	v_lshlrev_b32_e32 v140, 16, v190
	v_and_b32_e32 v141, 0xffff0000, v190
	v_lshlrev_b32_e32 v142, 16, v191
	v_and_b32_e32 v143, 0xffff0000, v191
	v_pk_add_f32 v[42:43], v[42:43], v[140:141]
	v_pk_add_f32 v[44:45], v[44:45], v[142:143]
	v_cvt_pk_bf16_f32 v188, v46, v47
	v_cvt_pk_bf16_f32 v189, v48, v49
	v_cvt_pk_bf16_f32 v190, v42, v43
	v_cvt_pk_bf16_f32 v191, v44, v45
	ds_write_b64 v235, v[188:189]
	ds_write_b64 v240, v[190:191]
	ds_read_b128 v[188:191], v234
	s_waitcnt vmcnt(13)
	ds_write_b128 v234, v[196:199]
	ds_read_b64 v[196:197], v235
	ds_read_b64 v[198:199], v240
	v_mul_f32_e32 v140, v46, v46
	v_mul_f32_e32 v141, v42, v42
	v_fmac_f32_e32 v140, v47, v47
	v_fmac_f32_e32 v141, v43, v43
	v_fmac_f32_e32 v140, v48, v48
	v_fmac_f32_e32 v141, v44, v44
	v_fmac_f32_e32 v140, v49, v49
	v_fmac_f32_e32 v141, v45, v45
	v_add_f32_e32 v138, v140, v141
	s_waitcnt lgkmcnt(3)
	global_store_dwordx4 v[222:223], v[188:191], off
	v_lshlrev_b32_e32 v140, 16, v192
	v_and_b32_e32 v141, 0xffff0000, v192
	v_lshlrev_b32_e32 v142, 16, v193
	v_and_b32_e32 v143, 0xffff0000, v193
	v_pk_add_f32 v[38:39], v[38:39], v[140:141]
	v_pk_add_f32 v[40:41], v[40:41], v[142:143]
	v_lshlrev_b32_e32 v140, 16, v194
	v_and_b32_e32 v141, 0xffff0000, v194
	v_lshlrev_b32_e32 v142, 16, v195
	v_and_b32_e32 v143, 0xffff0000, v195
	v_pk_add_f32 v[34:35], v[34:35], v[140:141]
	v_pk_add_f32 v[36:37], v[36:37], v[142:143]
	v_cvt_pk_bf16_f32 v192, v38, v39
	v_cvt_pk_bf16_f32 v193, v40, v41
	v_cvt_pk_bf16_f32 v194, v34, v35
	v_cvt_pk_bf16_f32 v195, v36, v37
	ds_write_b64 v235, v[192:193]
	ds_write_b64 v240, v[194:195]
	ds_read_b128 v[192:195], v234
	s_waitcnt vmcnt(13)
	ds_write_b128 v234, v[200:203]
	ds_read_b64 v[200:201], v235
	ds_read_b64 v[202:203], v240
	v_mul_f32_e32 v140, v38, v38
	v_mul_f32_e32 v141, v34, v34
	v_fmac_f32_e32 v140, v39, v39
	v_fmac_f32_e32 v141, v35, v35
	v_fmac_f32_e32 v140, v40, v40
	v_fmac_f32_e32 v141, v36, v36
	v_fmac_f32_e32 v140, v41, v41
	v_fmac_f32_e32 v141, v37, v37
	v_add_f32_e32 v139, v140, v141
	v_add_f32_e32 v46, v138, v139
	s_waitcnt lgkmcnt(3)
	global_store_dwordx4 v[222:223], v[192:195], off offset:256
	v_lshlrev_b32_e32 v140, 16, v196
	v_and_b32_e32 v141, 0xffff0000, v196
	v_lshlrev_b32_e32 v142, 16, v197
	v_and_b32_e32 v143, 0xffff0000, v197
	v_pk_add_f32 v[30:31], v[30:31], v[140:141]
	v_pk_add_f32 v[32:33], v[32:33], v[142:143]
	v_lshlrev_b32_e32 v140, 16, v198
	v_and_b32_e32 v141, 0xffff0000, v198
	v_lshlrev_b32_e32 v142, 16, v199
	v_and_b32_e32 v143, 0xffff0000, v199
	v_pk_add_f32 v[26:27], v[26:27], v[140:141]
	v_pk_add_f32 v[28:29], v[28:29], v[142:143]
	v_cvt_pk_bf16_f32 v196, v30, v31
	v_cvt_pk_bf16_f32 v197, v32, v33
	v_cvt_pk_bf16_f32 v198, v26, v27
	v_cvt_pk_bf16_f32 v199, v28, v29
	ds_write_b64 v235, v[196:197]
	ds_write_b64 v240, v[198:199]
	ds_read_b128 v[196:199], v234
	s_waitcnt vmcnt(13)
; __device__ __forceinline__ unsigned cvt_pk_bf16(float lo, float hi) { f32x2_t v = {lo, hi}; bf16x2_t b = __builtin_convertvector(v, bf16x2_t); return __builtin_bit_cast(unsigned, b); }
;     __device__ __forceinline__ void operator()(const f32x4 (&acc)[2][2][4][2], const Unit& u, int wr, int wc, int fr, int fq) const {
;     ...
;         for (int ai = 0; ai < 2; ++ai)
; #pragma unroll
;             for (int m = 0; m < 4; ++m) { const int row = row0 + ai * HALF + m * 16; const size_t off = (size_t)row * 1024 + col0; float q = 0.f;
; #pragma unroll
;                 for (int bj = 0; bj < 2; ++bj)
; #pragma unroll
;                     for (int n = 0; n < 2; ++n) { const size_t o2 = off + bj * HALF + n * 16; const u32x2v b = bs[ai][m][bj][n];
;                         const f32x4 bf = {__builtin_bit_cast(float, b.x << 16), __builtin_bit_cast(float, b.x & 0xffff0000u), __builtin_bit_cast(float, b.y << 16), __builtin_bit_cast(float, b.y & 0xffff0000u)};
;                         const f32x4 o = bf + acc[ai][bj][m][n];
;                         u32x2v w; w.x = cvt_pk_bf16(o[0], o[1]); w.y = cvt_pk_bf16(o[2], o[3]); *(u32x2v*)(hb + o2) = w;
;                         q += (o[0] * o[0] + o[1] * o[1]) + (o[2] * o[2] + o[3] * o[3]); }
;                 q += __shfl_xor(q, 16); q += __shfl_xor(q, 32);
;                 if (fq == 0) ssq[(size_t)(4 * u.pn + wc) * 16384 + row] = q; }
	ds_write_b128 v234, v[204:207]
	ds_read_b64 v[204:205], v235
	ds_read_b64 v[206:207], v240
	v_mul_f32_e32 v140, v30, v30
	v_mul_f32_e32 v141, v26, v26
	v_fmac_f32_e32 v140, v31, v31
	v_fmac_f32_e32 v141, v27, v27
	v_fmac_f32_e32 v140, v32, v32
	v_fmac_f32_e32 v141, v28, v28
	v_fmac_f32_e32 v140, v33, v33
	v_fmac_f32_e32 v141, v29, v29
	v_add_f32_e32 v138, v140, v141
	s_waitcnt lgkmcnt(3)
	global_store_dwordx4 v[224:225], v[196:199], off
	v_lshlrev_b32_e32 v140, 16, v200
	v_and_b32_e32 v141, 0xffff0000, v200
	v_lshlrev_b32_e32 v142, 16, v201
	v_and_b32_e32 v143, 0xffff0000, v201
	v_pk_add_f32 v[22:23], v[22:23], v[140:141]
	v_pk_add_f32 v[24:25], v[24:25], v[142:143]
	v_lshlrev_b32_e32 v140, 16, v202
	v_and_b32_e32 v141, 0xffff0000, v202
	v_lshlrev_b32_e32 v142, 16, v203
	v_and_b32_e32 v143, 0xffff0000, v203
	v_pk_add_f32 v[18:19], v[18:19], v[140:141]
	v_pk_add_f32 v[20:21], v[20:21], v[142:143]
	v_cvt_pk_bf16_f32 v200, v22, v23
	v_cvt_pk_bf16_f32 v201, v24, v25
	v_cvt_pk_bf16_f32 v202, v18, v19
	v_cvt_pk_bf16_f32 v203, v20, v21
	ds_write_b64 v235, v[200:201]
	ds_write_b64 v240, v[202:203]
	ds_read_b128 v[200:203], v234
	s_waitcnt vmcnt(13)
	ds_write_b128 v234, v[208:211]
	ds_read_b64 v[208:209], v235
	ds_read_b64 v[210:211], v240
	v_mul_f32_e32 v140, v22, v22
	v_mul_f32_e32 v141, v18, v18
	v_fmac_f32_e32 v140, v23, v23
	v_fmac_f32_e32 v141, v19, v19
	v_fmac_f32_e32 v140, v24, v24
	v_fmac_f32_e32 v141, v20, v20
	v_fmac_f32_e32 v140, v25, v25
	v_fmac_f32_e32 v141, v21, v21
	v_add_f32_e32 v139, v140, v141
	v_add_f32_e32 v30, v138, v139
	s_waitcnt lgkmcnt(3)
	global_store_dwordx4 v[224:225], v[200:203], off offset:256
	v_lshlrev_b32_e32 v140, 16, v204
	v_and_b32_e32 v141, 0xffff0000, v204
	v_lshlrev_b32_e32 v142, 16, v205
	v_and_b32_e32 v143, 0xffff0000, v205
	v_pk_add_f32 v[14:15], v[14:15], v[140:141]
	v_pk_add_f32 v[16:17], v[16:17], v[142:143]
	v_lshlrev_b32_e32 v140, 16, v206
	v_and_b32_e32 v141, 0xffff0000, v206
	v_lshlrev_b32_e32 v142, 16, v207
	v_and_b32_e32 v143, 0xffff0000, v207
	v_pk_add_f32 v[10:11], v[10:11], v[140:141]
	v_pk_add_f32 v[12:13], v[12:13], v[142:143]
	v_cvt_pk_bf16_f32 v204, v14, v15
	v_cvt_pk_bf16_f32 v205, v16, v17
	v_cvt_pk_bf16_f32 v206, v10, v11
	v_cvt_pk_bf16_f32 v207, v12, v13
	ds_write_b64 v235, v[204:205]
	ds_write_b64 v240, v[206:207]
	ds_read_b128 v[204:207], v234
	v_mul_f32_e32 v140, v14, v14
	v_mul_f32_e32 v141, v10, v10
	v_fmac_f32_e32 v140, v15, v15
	v_fmac_f32_e32 v141, v11, v11
	v_fmac_f32_e32 v140, v16, v16
	v_fmac_f32_e32 v141, v12, v12
	v_fmac_f32_e32 v140, v17, v17
	v_fmac_f32_e32 v141, v13, v13
	v_add_f32_e32 v138, v140, v141
	s_waitcnt lgkmcnt(0)
	global_store_dwordx4 v[226:227], v[204:207], off
	v_lshlrev_b32_e32 v140, 16, v208
	v_and_b32_e32 v141, 0xffff0000, v208
	v_lshlrev_b32_e32 v142, 16, v209
	v_and_b32_e32 v143, 0xffff0000, v209
	v_pk_add_f32 v[6:7], v[6:7], v[140:141]
	v_pk_add_f32 v[8:9], v[8:9], v[142:143]
	v_lshlrev_b32_e32 v140, 16, v210
	v_and_b32_e32 v141, 0xffff0000, v210
	v_lshlrev_b32_e32 v142, 16, v211
	v_and_b32_e32 v143, 0xffff0000, v211
	v_pk_add_f32 v[2:3], v[2:3], v[140:141]
	v_pk_add_f32 v[4:5], v[4:5], v[142:143]
	v_cvt_pk_bf16_f32 v208, v6, v7
	v_cvt_pk_bf16_f32 v209, v8, v9
	v_cvt_pk_bf16_f32 v210, v2, v3
	v_cvt_pk_bf16_f32 v211, v4, v5
	ds_write_b64 v235, v[208:209]
	ds_write_b64 v240, v[210:211]
	ds_read_b128 v[208:211], v234
	v_mul_f32_e32 v140, v6, v6
	v_mul_f32_e32 v141, v2, v2
	v_fmac_f32_e32 v140, v7, v7
	v_fmac_f32_e32 v141, v3, v3
	v_fmac_f32_e32 v140, v8, v8
	v_fmac_f32_e32 v141, v4, v4
	v_fmac_f32_e32 v140, v9, v9
	v_fmac_f32_e32 v141, v5, v5
	v_add_f32_e32 v139, v140, v141
	v_add_f32_e32 v14, v138, v139
	s_waitcnt lgkmcnt(0)
	global_store_dwordx4 v[226:227], v[208:211], off offset:256
	ds_bpermute_b32 v127, v232, v126
	ds_bpermute_b32 v111, v232, v110
	ds_bpermute_b32 v95, v232, v94
	ds_bpermute_b32 v79, v232, v78
	ds_bpermute_b32 v63, v232, v62
	ds_bpermute_b32 v47, v232, v46
	ds_bpermute_b32 v31, v232, v30
	ds_bpermute_b32 v15, v232, v14
	s_waitcnt lgkmcnt(0)
	v_add_f32_e32 v126, v126, v127
	v_add_f32_e32 v110, v110, v111
	v_add_f32_e32 v94, v94, v95
	v_add_f32_e32 v78, v78, v79
	v_add_f32_e32 v62, v62, v63
	v_add_f32_e32 v46, v46, v47
	v_add_f32_e32 v30, v30, v31
	v_add_f32_e32 v14, v14, v15
	ds_bpermute_b32 v127, v233, v126
	ds_bpermute_b32 v111, v233, v110
	ds_bpermute_b32 v95, v233, v94
	ds_bpermute_b32 v79, v233, v78
	ds_bpermute_b32 v63, v233, v62
	ds_bpermute_b32 v47, v233, v46
	ds_bpermute_b32 v31, v233, v30
	ds_bpermute_b32 v15, v233, v14
	s_waitcnt lgkmcnt(0)
	v_add_f32_e32 v126, v126, v127
	v_add_f32_e32 v110, v110, v111
	v_add_f32_e32 v94, v94, v95
	v_add_f32_e32 v78, v78, v79
	v_add_f32_e32 v62, v62, v63
	v_add_f32_e32 v46, v46, v47
	v_add_f32_e32 v30, v30, v31
	v_add_f32_e32 v14, v14, v15
	s_lshl_b32 s6, s23, 2
	s_or_b32 s6, s6, s12
	s_ashr_i32 s7, s6, 31
	s_lshl_b64 s[6:7], s[6:7], 16
	v_readlane_b32 s10, v252, 15
	v_readlane_b32 s11, v252, 16
	s_add_u32 s10, s10, s6
	s_addc_u32 s11, s11, s7
	s_lshl_b32 s6, s24, 8
	s_add_i32 s6, s6, s16
	v_add_u32_e32 v136, s6, v228
	v_ashrrev_i32_e32 v137, 31, v136
	v_lshl_add_u64 v[140:141], v[136:137], 2, s[10:11]
	s_and_saveexec_b64 s[8:9], s[38:39]
	global_store_dword v[140:141], v126, off
	global_store_dword v[140:141], v110, off offset:64
	global_store_dword v[140:141], v94, off offset:128
	global_store_dword v[140:141], v78, off offset:192
	global_store_dword v[140:141], v62, off offset:512
	global_store_dword v[140:141], v46, off offset:576
	global_store_dword v[140:141], v30, off offset:640
	global_store_dword v[140:141], v14, off offset:704
